# PEER combine loop: next token's 16 score/index loads prefetched with precomputed lane offsets and SGPR row bases; counted wait excludes the gate stores
# baseline (speedup 1.0000x reference)
; DI int TID() { int t = threadIdx.x; asm volatile("" : "+v"(t)); return t; }
; DI void phase_peer(const Params& p, int l, int bid, int nblk) {
;     ...
;   for (int row = bid * 4 + w; row < ROWS; row += nblk * 4) {
;     const int b = row / TPB, pos = row % TPB;
;     if (l == 1 && pos < CTXL) continue;
;     const int lane = TID() & 63;
;     const int head = lane >> 3, sub = lane & 7;
;     const float* tv1 = TV + ((size_t)row * 16 + head * 2) * 16;
;     const float* tv2 = tv1 + 16;
;     const int* ti1 = TI + ((size_t)row * 16 + head * 2) * 16;
;     const int* ti2 = ti1 + 16;
;     const int t1lo = ti1[sub], t1hi = ti1[sub + 8], t2lo = ti2[sub], t2hi = ti2[sub + 8];
.Lpeer_a_again:
	v_mov_b32_e32 v0, v218
	s_mov_b32 s55, 0
	s_mov_b32 s66, 0
	v_readlane_b32 s0, v255, 58
	v_ashrrev_i32_e32 v0, 6, v0
	v_readlane_b32 s1, v255, 59
	v_add_u32_e32 v64, s0, v0
	s_mov_b32 s0, 0x9000
	v_cmp_gt_i32_e32 vcc, s0, v64
	s_and_saveexec_b64 s[50:51], vcc
	s_cbranch_execz .LBB0_1558
	s_mov_b64 s[62:63], 0
	v_readlane_b32 s28, v255, 50
	v_readlane_b32 s29, v255, 51
	v_and_b32_e32 v20, 7, v218
	v_bfe_u32 v21, v218, 3, 3
	v_lshlrev_b32_e32 v22, 7, v21
	v_lshlrev_b32_e32 v23, 2, v20
	v_lshl_add_u32 v24, v20, 2, v22
	v_mov_b32_e32 v25, v22
	s_mov_b32 s23, 0x33322222
	v_bfe_u32 v26, s23, v23, 2
	v_lshl_add_u32 v26, v26, 2, v22
	s_mov_b32 s23, 0x21043210
	v_bfe_u32 v27, s23, v23, 3
	v_lshl_add_u32 v27, v27, 2, v22
	s_mov_b32 s23, 0x66554443
	v_bfe_u32 v28, s23, v23, 3
	v_lshl_add_u32 v28, v28, 2, v22
	s_mov_b32 s23, 0x10102103
	v_bfe_u32 v29, s23, v23, 2
	v_lshl_add_u32 v29, v29, 2, v22
	s_mov_b32 s23, 0xdcba9877
	v_bfe_u32 v30, s23, v23, 4
	v_lshl_add_u32 v30, v30, 2, v22
	v_cmp_eq_u32_e32 vcc, 1, v20
	s_nop 1
	v_cndmask_b32_e64 v31, 0, 4, vcc
	v_add_u32_e32 v31, v31, v22
	s_mov_b32 s23, 0xfe
	v_bfe_u32 v32, s23, v23, 4
	v_lshl_add_u32 v32, v32, 2, v22
	v_readfirstlane_b32 s22, v64
	s_lshl_b32 s22, s22, 10
	s_add_u32 s24, s68, s22
	s_addc_u32 s25, s69, 0
	s_add_u32 s26, s28, s22
	s_addc_u32 s27, s29, 0
	global_load_dword v34, v24, s[26:27]
	global_load_dword v35, v24, s[26:27] offset:32
	global_load_dword v36, v24, s[26:27] offset:64
	global_load_dword v37, v24, s[26:27] offset:96
	global_load_dwordx2 v[38:39], v25, s[24:25]
	global_load_dword v40, v24, s[24:25] offset:64
	global_load_dword v41, v24, s[24:25] offset:96
	global_load_dword v42, v26, s[24:25]
	global_load_dword v43, v27, s[24:25] offset:64
	global_load_dword v44, v28, s[24:25]
	global_load_dword v45, v29, s[24:25] offset:64
	global_load_dword v46, v30, s[24:25]
	global_load_dword v47, v31, s[24:25] offset:64
	global_load_dword v48, v32, s[24:25]
	global_load_dword v49, v25, s[24:25] offset:64
	s_mov_b32 s30, 0
	s_branch .LBB0_1509

; DI int TID() { int t = threadIdx.x; asm volatile("" : "+v"(t)); return t; }
; DI void phase_peer(const Params& p, int l, int bid, int nblk) {
;     ...
;   for (int row = bid * 4 + w; row < ROWS; row += nblk * 4) {
;     const int b = row / TPB, pos = row % TPB;
;     if (l == 1 && pos < CTXL) continue;
;     const int lane = TID() & 63;
;     const int head = lane >> 3, sub = lane & 7;
;     const float* tv1 = TV + ((size_t)row * 16 + head * 2) * 16;
;     const float* tv2 = tv1 + 16;
;     const int* ti1 = TI + ((size_t)row * 16 + head * 2) * 16;
;     const int* ti2 = ti1 + 16;
;     const int t1lo = ti1[sub], t1hi = ti1[sub + 8], t2lo = ti2[sub], t2hi = ti2[sub + 8];
.LBB0_1509:
	s_cmp_eq_u32 s30, 0
	s_cbranch_scc1 .Lpa_w0
	s_waitcnt vmcnt(2)
	s_branch .Lpa_wd

; DI int TID() { int t = threadIdx.x; asm volatile("" : "+v"(t)); return t; }
; DI void phase_peer(const Params& p, int l, int bid, int nblk) {
;     ...
;   for (int row = bid * 4 + w; row < ROWS; row += nblk * 4) {
;     const int b = row / TPB, pos = row % TPB;
;     if (l == 1 && pos < CTXL) continue;
;     const int lane = TID() & 63;
;     const int head = lane >> 3, sub = lane & 7;
;     const float* tv1 = TV + ((size_t)row * 16 + head * 2) * 16;
;     const float* tv2 = tv1 + 16;
;     const int* ti1 = TI + ((size_t)row * 16 + head * 2) * 16;
;     const int* ti2 = ti1 + 16;
;     const int t1lo = ti1[sub], t1hi = ti1[sub + 8], t2lo = ti2[sub], t2hi = ti2[sub + 8];
;     u32 ck[7];
; #pragma unroll
;     for (int s = 0; s < 7; ++s) {
;       const int c = sub + 8 * s;
;       if (c < 50) {
;         const u32 u = __float_as_uint(tv1[cand_a(c)] + tv2[cand_b(c)]);
;         const u32 ord = (u & 0x80000000u) ? ~u : (u | 0x80000000u);
;         ck[s] = (ord & ~63u) | (u32)(63 - c);
;       } else ck[s] = 0u;
;     }
.Lpa_wd:
	v_mov_b32_e32 v50, v34
	v_mov_b32_e32 v51, v35
	v_mov_b32_e32 v52, v36
	v_mov_b32_e32 v53, v37
	v_mov_b32_e32 v54, v38
	v_mov_b32_e32 v55, v39
	v_mov_b32_e32 v56, v40
	v_mov_b32_e32 v57, v41
	v_mov_b32_e32 v58, v42
	v_mov_b32_e32 v59, v43
	v_mov_b32_e32 v60, v44
	v_mov_b32_e32 v61, v45
	v_mov_b32_e32 v62, v46
	v_mov_b32_e32 v63, v47
	v_mov_b32_e32 v66, v48
	v_mov_b32_e32 v67, v49
	v_readfirstlane_b32 s22, v64
	s_add_i32 s22, s22, 0x800
	s_lshl_b32 s22, s22, 10
	s_add_u32 s24, s68, s22
	s_addc_u32 s25, s69, 0
	s_add_u32 s26, s28, s22
	s_addc_u32 s27, s29, 0
	global_load_dword v34, v24, s[26:27]
	global_load_dword v35, v24, s[26:27] offset:32
	global_load_dword v36, v24, s[26:27] offset:64
	global_load_dword v37, v24, s[26:27] offset:96
	global_load_dwordx2 v[38:39], v25, s[24:25]
	global_load_dword v40, v24, s[24:25] offset:64
	global_load_dword v41, v24, s[24:25] offset:96
	global_load_dword v42, v26, s[24:25]
	global_load_dword v43, v27, s[24:25] offset:64
	global_load_dword v44, v28, s[24:25]
	global_load_dword v45, v29, s[24:25] offset:64
	global_load_dword v46, v30, s[24:25]
	global_load_dword v47, v31, s[24:25] offset:64
	global_load_dword v48, v32, s[24:25]
	global_load_dword v49, v25, s[24:25] offset:64
	s_mov_b32 s30, 0
	v_mul_hi_i32 v0, v64, s33
	v_lshrrev_b32_e32 v1, 31, v0
	v_ashrrev_i32_e32 v0, 9, v0
	v_add_u32_e32 v0, v0, v1
	v_mul_i32_i24_e32 v0, 0x900, v0
	v_sub_u32_e32 v0, v64, v0
	s_movk_i32 s0, 0xff
	v_cmp_lt_i32_e32 vcc, s0, v0
	s_xor_b64 s[0:1], s[70:71], -1
	s_or_b64 s[0:1], s[0:1], vcc
	s_and_saveexec_b64 s[64:65], s[0:1]
	s_cbranch_execz .LBB0_1508
	v_mov_b32_e32 v14, v218
	v_ashrrev_i32_e32 v65, 31, v64
	v_lshlrev_b64 v[0:1], 10, v[64:65]
	v_bfe_u32 v84, v14, 3, 3
	v_readlane_b32 s0, v255, 50
	v_and_b32_e32 v20, 7, v14
	v_lshl_or_b32 v0, v84, 7, v0
	v_readlane_b32 s1, v255, 51
	v_lshl_add_u64 v[4:5], s[68:69], 0, v[0:1]
	v_lshlrev_b32_e32 v172, 2, v20
	v_lshl_add_u64 v[0:1], s[0:1], 0, v[0:1]
	s_mov_b32 s0, 0x76543210
	v_bfe_u32 v2, s0, v172, 3
	v_lshlrev_b32_e32 v2, 2, v2
	v_mov_b32_e32 v3, v173
	v_lshl_add_u64 v[0:1], v[0:1], 0, v[172:173]
	v_lshl_add_u64 v[2:3], v[4:5], 0, v[2:3]
	s_mov_b32 s0, 0xfedcba98
	v_mov_b32_e32 v17, v50
	v_mov_b32_e32 v18, v51
	v_mov_b32_e32 v15, v52
	v_mov_b32_e32 v16, v53
	s_nop 0
	v_mov_b32_e32 v0, v54
	v_mov_b32_e32 v1, v55
	v_mov_b32_e32 v7, v173
	v_mov_b32_e32 v3, v56
	v_bfe_u32 v2, s0, v172, 4
	v_lshlrev_b32_e32 v6, 2, v2
	v_lshl_add_u64 v[6:7], v[4:5], 0, v[6:7]
	s_mov_b32 s0, 0x33322222
	v_mov_b32_e32 v2, v57
	v_bfe_u32 v6, s0, v172, 2
	v_lshlrev_b32_e32 v6, 2, v6
	v_mov_b32_e32 v7, v173
	v_lshl_add_u64 v[6:7], v[4:5], 0, v[6:7]
	s_mov_b32 s0, 0x21043210
	v_mov_b32_e32 v8, v58
	v_bfe_u32 v6, s0, v172, 3
	v_lshlrev_b32_e32 v6, 2, v6
	v_mov_b32_e32 v7, v173
	v_lshl_add_u64 v[6:7], v[4:5], 0, v[6:7]
	s_mov_b32 s0, 0x66554443
	v_mov_b32_e32 v12, v59
	v_bfe_u32 v6, s0, v172, 3
	v_lshlrev_b32_e32 v6, 2, v6
	v_mov_b32_e32 v7, v173
	v_lshl_add_u64 v[6:7], v[4:5], 0, v[6:7]
	s_mov_b32 s0, 0x10102103
	v_mov_b32_e32 v7, v60
	v_bfe_u32 v6, s0, v172, 2
	s_mov_b32 s0, 0xdcba9877
	v_lshlrev_b32_e32 v10, 2, v6
	v_bfe_u32 v6, s0, v172, 4
	v_mov_b32_e32 v11, v173
	v_lshlrev_b32_e32 v22, 2, v6
	v_mov_b32_e32 v23, v173
	v_cmp_eq_u32_e32 vcc, 1, v20
	v_lshl_add_u64 v[10:11], v[4:5], 0, v[10:11]
	v_lshl_add_u64 v[22:23], v[4:5], 0, v[22:23]
	v_cndmask_b32_e64 v9, 0, 1, vcc
	v_mov_b32_e32 v11, v61
	v_mov_b32_e32 v19, 0
	v_mov_b32_e32 v6, v62
	v_lshlrev_b32_e32 v22, 2, v9
	v_mov_b32_e32 v23, v173
	v_lshl_add_u64 v[22:23], v[4:5], 0, v[22:23]
	v_mov_b32_e32 v10, v63
	v_or_b32_e32 v9, 48, v20
	v_cmp_gt_u32_e64 s[0:1], 50, v9
	s_and_saveexec_b64 s[34:35], s[0:1]
	s_cbranch_execz .LBB0_1512
	s_movk_i32 s0, 0xfe
	v_bfe_u32 v9, s0, v172, 4
	v_lshlrev_b32_e32 v172, 2, v9
	v_lshl_add_u64 v[22:23], v[4:5], 0, v[172:173]
	v_mov_b32_e32 v9, v66
	s_nop 0
	v_mov_b32_e32 v4, v67
	v_add_f32_e32 v4, v9, v4
	v_not_b32_e32 v5, v4
	v_or_b32_e32 v9, 0x80000000, v4
	v_cmp_gt_i32_e64 s[0:1], 0, v4
	s_nop 1
	v_cndmask_b32_e64 v4, v9, v5, s[0:1]
	v_and_b32_e32 v4, 0xffffffc0, v4
	v_bitop3_b32 v19, v4, 15, v20 bitop3:0x36
.LBB0_1512:
	s_or_b64 exec, exec, s[34:35]
	v_pk_add_f32 v[4:5], v[0:1], v[2:3] op_sel_hi:[0,1]
	v_not_b32_e32 v0, v5
	v_or_b32_e32 v2, 0x80000000, v5
	v_cmp_gt_i32_e64 s[0:1], 0, v5
	v_or_b32_e32 v5, 0x80000000, v4
	v_or_b32_e32 v9, 8, v20
	v_cndmask_b32_e64 v0, v2, v0, s[0:1]
	v_and_b32_e32 v0, 0xffffffc0, v0
	v_sub_u32_e32 v21, v0, v20
	v_not_b32_e32 v0, v4
	v_cmp_gt_i32_e64 s[0:1], 0, v4
	v_mov_b32_e32 v13, v1
	v_or_b32_e32 v23, 24, v20
	v_cndmask_b32_e64 v0, v5, v0, s[0:1]
	v_and_b32_e32 v0, 0xffffffc0, v0
	v_sub_u32_e32 v22, v0, v9
	v_mov_b32_e32 v9, v3
	v_pk_add_f32 v[0:1], v[8:9], v[12:13]
	v_or_b32_e32 v5, 16, v20
	v_not_b32_e32 v3, v1
	v_or_b32_e32 v8, 0x80000000, v1
	v_cmp_gt_i32_e64 s[0:1], 0, v1
	v_or_b32_e32 v12, 32, v20
	v_or_b32_e32 v13, 40, v20
	v_cndmask_b32_e64 v1, v8, v3, s[0:1]
	v_and_b32_e32 v1, 0xffffffc0, v1
	v_sub_u32_e32 v8, v1, v5
	v_not_b32_e32 v1, v0
	v_or_b32_e32 v5, 0x80000000, v0
	v_cmp_gt_i32_e64 s[0:1], 0, v0
	v_add_u32_e32 v3, 63, v8
	v_add_u32_e32 v8, 64, v8
	v_cndmask_b32_e64 v0, v5, v1, s[0:1]
	v_and_b32_e32 v0, 0xffffffc0, v0
	v_sub_u32_e32 v9, v0, v23
	v_pk_add_f32 v[0:1], v[6:7], v[10:11]
	v_add_u32_e32 v11, 64, v22
	v_not_b32_e32 v6, v1
	v_or_b32_e32 v7, 0x80000000, v1
	v_cmp_gt_i32_e64 s[0:1], 0, v1
	v_or_b32_e32 v10, 0x80000000, v0
	v_add_u32_e32 v5, 63, v9
	v_cndmask_b32_e64 v1, v7, v6, s[0:1]
	v_not_b32_e32 v7, v0
	v_cmp_gt_i32_e64 s[0:1], 0, v0
	v_and_b32_e32 v1, 0xffffffc0, v1
	v_sub_u32_e32 v1, v1, v12
	v_cndmask_b32_e64 v0, v10, v7, s[0:1]
; template <int CTRL> DI int dpp_i(int v) { return __builtin_amdgcn_mov_dpp(v, CTRL, 0xF, 0xF, true); }
; DI void phase_peer(const Params& p, int l, int bid, int nblk) {
;     ...
;     float w0v = 0.f, w1v = 0.f, mx = 0.f;
;     int w0c = 0, w1c = 0;
;     u32 prevk = 0xFFFFFFFFu;
; #pragma unroll
;     for (int r = 0; r < 16; ++r) {
;       u32 m = 0u;
; #pragma unroll
;       for (int s = 0; s < 7; ++s) { const u32 d = ck[s] - prevk; m = d > m ? d : m; }
;       { const u32 ov = (u32)dpp_i<DPP_XOR1>((int)m); m = ov > m ? ov : m; }
;       { const u32 ov = (u32)dpp_i<DPP_XOR2>((int)m); m = ov > m ? ov : m; }
;       { const u32 ov = (u32)dpp_i<DPP_MIRROR8>((int)m); m = ov > m ? ov : m; }
;       const u32 best = prevk + m;
;       prevk = best;
;       const u32 ordv = best & ~63u;
;       const float bv = __uint_as_float((ordv & 0x80000000u) ? (ordv & 0x7FFFFFFFu) : ~ordv);
;       const int bc = 63 - (int)(best & 63u);
;       if (r == 0) mx = bv;
;       if (sub == (r & 7)) {
;         if (r < 8) { w0v = bv; w0c = bc; } else { w1v = bv; w1c = bc; }
;       }
;     }
	v_and_b32_e32 v0, 0xffffffc0, v0
	v_add_u32_e32 v10, 64, v21
	v_add_u32_e32 v6, 63, v1
	v_sub_u32_e32 v0, v0, v13
	v_max3_u32 v8, v8, v11, v10
	v_add_u32_e32 v9, 64, v9
	v_add_u32_e32 v1, 64, v1
	v_add_u32_e32 v7, 63, v0
	v_max3_u32 v1, v1, v9, v8
	v_add_u32_e32 v0, 64, v0
	v_add_u32_e32 v8, 1, v19
	v_max3_u32 v0, v8, v0, v1
	v_add_u32_e32 v2, 63, v21
	v_add_u32_e32 v4, 63, v22
	v_max_u32_dpp v0, v0, v0 quad_perm:[1,0,3,2] row_mask:0xf bank_mask:0xf bound_ctrl:1
	v_cmp_eq_u32_e64 s[46:47], 0, v20
	s_nop 0
	v_max_u32_dpp v0, v0, v0 quad_perm:[2,3,0,1] row_mask:0xf bank_mask:0xf bound_ctrl:1
	s_nop 1
	v_max_u32_dpp v0, v0, v0 row_half_mirror row_mask:0xf bank_mask:0xf bound_ctrl:1
	v_add_u32_e32 v9, -1, v0
	v_sub_u32_e32 v10, v2, v9
	v_sub_u32_e32 v11, v4, v9
	v_sub_u32_e32 v12, v3, v9
	v_max3_u32 v10, v12, v11, v10
	v_sub_u32_e32 v11, v5, v9
	v_sub_u32_e32 v12, v6, v9
	v_max3_u32 v10, v12, v11, v10
	v_sub_u32_e32 v11, v7, v9
	v_sub_u32_e32 v12, v19, v9
	v_max3_u32 v10, v12, v11, v10
	v_and_b32_e32 v0, 0x7fffffc0, v9
	v_bitop3_b32 v1, v9, 63, v9 bitop3:0xcf
	v_max_u32_dpp v10, v10, v10 quad_perm:[1,0,3,2] row_mask:0xf bank_mask:0xf bound_ctrl:1
	v_cmp_gt_i32_e64 s[0:1], 0, v9
	s_nop 0
	v_max_u32_dpp v10, v10, v10 quad_perm:[2,3,0,1] row_mask:0xf bank_mask:0xf bound_ctrl:1
	v_cndmask_b32_e64 v1, v1, v0, s[0:1]
	v_bitop3_b32 v0, v9, 63, v9 bitop3:0xc
	v_max_u32_dpp v10, v10, v10 row_half_mirror row_mask:0xf bank_mask:0xf bound_ctrl:1
	v_cndmask_b32_e64 v0, 0, v0, s[46:47]
	v_cndmask_b32_e64 v8, 0, v1, s[46:47]
	v_add_u32_e32 v9, v10, v9
	s_and_saveexec_b64 s[34:35], vcc
	v_and_b32_e32 v0, 0x7fffffc0, v9
	v_bitop3_b32 v8, v9, 63, v9 bitop3:0xcf
	v_cmp_gt_i32_e64 s[0:1], 0, v9
	s_nop 1
	v_cndmask_b32_e64 v8, v8, v0, s[0:1]
	v_bitop3_b32 v0, v9, 63, v9 bitop3:0xc
	s_or_b64 exec, exec, s[34:35]
	v_sub_u32_e32 v10, v2, v9
	v_sub_u32_e32 v11, v4, v9
	v_sub_u32_e32 v12, v3, v9
	v_max3_u32 v10, v12, v11, v10
	v_sub_u32_e32 v11, v5, v9
	v_sub_u32_e32 v12, v6, v9
	v_max3_u32 v10, v12, v11, v10
	v_sub_u32_e32 v11, v7, v9
	v_sub_u32_e32 v12, v19, v9
	v_max3_u32 v10, v12, v11, v10
	v_cmp_eq_u32_e64 s[0:1], 2, v20
	s_nop 0
	v_max_u32_dpp v10, v10, v10 quad_perm:[1,0,3,2] row_mask:0xf bank_mask:0xf bound_ctrl:1
	s_nop 1
	v_max_u32_dpp v10, v10, v10 quad_perm:[2,3,0,1] row_mask:0xf bank_mask:0xf bound_ctrl:1
	s_nop 1
	v_max_u32_dpp v10, v10, v10 row_half_mirror row_mask:0xf bank_mask:0xf bound_ctrl:1
	v_add_u32_e32 v9, v10, v9
	s_and_saveexec_b64 s[34:35], s[0:1]
	v_and_b32_e32 v0, 0x7fffffc0, v9
	v_bitop3_b32 v8, v9, 63, v9 bitop3:0xcf
	v_cmp_gt_i32_e64 s[36:37], 0, v9
	s_nop 1
	v_cndmask_b32_e64 v8, v8, v0, s[36:37]
	v_bitop3_b32 v0, v9, 63, v9 bitop3:0xc
	s_or_b64 exec, exec, s[34:35]
	v_sub_u32_e32 v10, v2, v9
	v_sub_u32_e32 v11, v4, v9
	v_sub_u32_e32 v12, v3, v9
	v_max3_u32 v10, v12, v11, v10
	v_sub_u32_e32 v11, v5, v9
	v_sub_u32_e32 v12, v6, v9
	v_max3_u32 v10, v12, v11, v10
	v_sub_u32_e32 v11, v7, v9
	v_sub_u32_e32 v12, v19, v9
	v_max3_u32 v10, v12, v11, v10
	v_cmp_eq_u32_e64 s[36:37], 3, v20
	s_nop 0
	v_max_u32_dpp v10, v10, v10 quad_perm:[1,0,3,2] row_mask:0xf bank_mask:0xf bound_ctrl:1
	s_nop 1
	v_max_u32_dpp v10, v10, v10 quad_perm:[2,3,0,1] row_mask:0xf bank_mask:0xf bound_ctrl:1
	s_nop 1
	v_max_u32_dpp v10, v10, v10 row_half_mirror row_mask:0xf bank_mask:0xf bound_ctrl:1
	v_add_u32_e32 v9, v10, v9
	s_and_saveexec_b64 s[34:35], s[36:37]
	v_and_b32_e32 v0, 0x7fffffc0, v9
	v_bitop3_b32 v8, v9, 63, v9 bitop3:0xcf
	v_cmp_gt_i32_e64 s[38:39], 0, v9
	s_nop 1
	v_cndmask_b32_e64 v8, v8, v0, s[38:39]
	v_bitop3_b32 v0, v9, 63, v9 bitop3:0xc
	s_or_b64 exec, exec, s[34:35]
	v_sub_u32_e32 v10, v2, v9
	v_sub_u32_e32 v11, v4, v9
	v_sub_u32_e32 v12, v3, v9
	v_max3_u32 v10, v12, v11, v10
	v_sub_u32_e32 v11, v5, v9
	v_sub_u32_e32 v12, v6, v9
	v_max3_u32 v10, v12, v11, v10
	v_sub_u32_e32 v11, v7, v9
	v_sub_u32_e32 v12, v19, v9
	v_max3_u32 v10, v12, v11, v10
	v_cmp_eq_u32_e64 s[38:39], 4, v20
	s_nop 0
	v_max_u32_dpp v10, v10, v10 quad_perm:[1,0,3,2] row_mask:0xf bank_mask:0xf bound_ctrl:1
	s_nop 1
	v_max_u32_dpp v10, v10, v10 quad_perm:[2,3,0,1] row_mask:0xf bank_mask:0xf bound_ctrl:1
	s_nop 1
	v_max_u32_dpp v10, v10, v10 row_half_mirror row_mask:0xf bank_mask:0xf bound_ctrl:1
	v_add_u32_e32 v9, v10, v9
	s_and_saveexec_b64 s[34:35], s[38:39]
	v_and_b32_e32 v0, 0x7fffffc0, v9
	v_bitop3_b32 v8, v9, 63, v9 bitop3:0xcf
	v_cmp_gt_i32_e64 s[40:41], 0, v9
	s_nop 1
	v_cndmask_b32_e64 v8, v8, v0, s[40:41]
	v_bitop3_b32 v0, v9, 63, v9 bitop3:0xc
	s_or_b64 exec, exec, s[34:35]
	v_sub_u32_e32 v10, v2, v9
	v_sub_u32_e32 v11, v4, v9
	v_sub_u32_e32 v12, v3, v9
	v_max3_u32 v10, v12, v11, v10
	v_sub_u32_e32 v11, v5, v9
	v_sub_u32_e32 v12, v6, v9
	v_max3_u32 v10, v12, v11, v10
	v_sub_u32_e32 v11, v7, v9
	v_sub_u32_e32 v12, v19, v9
	v_max3_u32 v10, v12, v11, v10
	v_cmp_eq_u32_e64 s[40:41], 5, v20
	s_nop 0
	v_max_u32_dpp v10, v10, v10 quad_perm:[1,0,3,2] row_mask:0xf bank_mask:0xf bound_ctrl:1
	s_nop 1
	v_max_u32_dpp v10, v10, v10 quad_perm:[2,3,0,1] row_mask:0xf bank_mask:0xf bound_ctrl:1
	s_nop 1
	v_max_u32_dpp v10, v10, v10 row_half_mirror row_mask:0xf bank_mask:0xf bound_ctrl:1
	v_add_u32_e32 v9, v10, v9
	s_and_saveexec_b64 s[34:35], s[40:41]
	v_and_b32_e32 v0, 0x7fffffc0, v9
	v_bitop3_b32 v8, v9, 63, v9 bitop3:0xcf
	v_cmp_gt_i32_e64 s[42:43], 0, v9
	s_nop 1
	v_cndmask_b32_e64 v8, v8, v0, s[42:43]
	v_bitop3_b32 v0, v9, 63, v9 bitop3:0xc
	s_or_b64 exec, exec, s[34:35]
	v_sub_u32_e32 v10, v2, v9
	v_sub_u32_e32 v11, v4, v9
	v_sub_u32_e32 v12, v3, v9
	v_max3_u32 v10, v12, v11, v10
	v_sub_u32_e32 v11, v5, v9
	v_sub_u32_e32 v12, v6, v9
	v_max3_u32 v10, v12, v11, v10
	v_sub_u32_e32 v11, v7, v9
; template <int CTRL> DI int dpp_i(int v) { return __builtin_amdgcn_mov_dpp(v, CTRL, 0xF, 0xF, true); }
; DI void phase_peer(const Params& p, int l, int bid, int nblk) {
;     ...
; #pragma unroll
;     for (int r = 0; r < 16; ++r) {
;       u32 m = 0u;
; #pragma unroll
;       for (int s = 0; s < 7; ++s) { const u32 d = ck[s] - prevk; m = d > m ? d : m; }
;       { const u32 ov = (u32)dpp_i<DPP_XOR1>((int)m); m = ov > m ? ov : m; }
;       { const u32 ov = (u32)dpp_i<DPP_XOR2>((int)m); m = ov > m ? ov : m; }
;       { const u32 ov = (u32)dpp_i<DPP_MIRROR8>((int)m); m = ov > m ? ov : m; }
;       const u32 best = prevk + m;
;       prevk = best;
;       const u32 ordv = best & ~63u;
;       const float bv = __uint_as_float((ordv & 0x80000000u) ? (ordv & 0x7FFFFFFFu) : ~ordv);
;       const int bc = 63 - (int)(best & 63u);
;       if (r == 0) mx = bv;
;       if (sub == (r & 7)) {
;         if (r < 8) { w0v = bv; w0c = bc; } else { w1v = bv; w1c = bc; }
;       }
;     }
	v_sub_u32_e32 v12, v19, v9
	v_max3_u32 v10, v12, v11, v10
	v_cmp_eq_u32_e64 s[42:43], 6, v20
	s_nop 0
	v_max_u32_dpp v10, v10, v10 quad_perm:[1,0,3,2] row_mask:0xf bank_mask:0xf bound_ctrl:1
	s_nop 1
	v_max_u32_dpp v10, v10, v10 quad_perm:[2,3,0,1] row_mask:0xf bank_mask:0xf bound_ctrl:1
	s_nop 1
	v_max_u32_dpp v10, v10, v10 row_half_mirror row_mask:0xf bank_mask:0xf bound_ctrl:1
	v_add_u32_e32 v9, v10, v9
	s_and_saveexec_b64 s[34:35], s[42:43]
	v_and_b32_e32 v0, 0x7fffffc0, v9
	v_bitop3_b32 v8, v9, 63, v9 bitop3:0xcf
	v_cmp_gt_i32_e64 s[44:45], 0, v9
	s_nop 1
	v_cndmask_b32_e64 v8, v8, v0, s[44:45]
	v_bitop3_b32 v0, v9, 63, v9 bitop3:0xc
	s_or_b64 exec, exec, s[34:35]
	v_sub_u32_e32 v10, v2, v9
	v_sub_u32_e32 v11, v4, v9
	v_sub_u32_e32 v12, v3, v9
	v_max3_u32 v10, v12, v11, v10
	v_sub_u32_e32 v11, v5, v9
	v_sub_u32_e32 v12, v6, v9
	v_max3_u32 v10, v12, v11, v10
	v_sub_u32_e32 v11, v7, v9
	v_sub_u32_e32 v12, v19, v9
	v_max3_u32 v10, v12, v11, v10
	v_cmp_eq_u32_e64 s[44:45], 7, v20
	s_nop 0
	v_max_u32_dpp v10, v10, v10 quad_perm:[1,0,3,2] row_mask:0xf bank_mask:0xf bound_ctrl:1
	s_nop 1
	v_max_u32_dpp v10, v10, v10 quad_perm:[2,3,0,1] row_mask:0xf bank_mask:0xf bound_ctrl:1
	s_nop 1
	v_max_u32_dpp v10, v10, v10 row_half_mirror row_mask:0xf bank_mask:0xf bound_ctrl:1
	v_add_u32_e32 v9, v10, v9
	s_and_saveexec_b64 s[34:35], s[44:45]
	v_and_b32_e32 v0, 0x7fffffc0, v9
	v_bitop3_b32 v8, v9, 63, v9 bitop3:0xcf
	v_cmp_gt_i32_e64 s[48:49], 0, v9
	s_nop 1
	v_cndmask_b32_e64 v8, v8, v0, s[48:49]
	v_bitop3_b32 v0, v9, 63, v9 bitop3:0xc
	s_or_b64 exec, exec, s[34:35]
	v_sub_u32_e32 v10, v2, v9
	v_sub_u32_e32 v11, v4, v9
	v_sub_u32_e32 v12, v3, v9
	v_max3_u32 v10, v12, v11, v10
	v_sub_u32_e32 v11, v5, v9
	v_sub_u32_e32 v12, v6, v9
	v_max3_u32 v10, v12, v11, v10
	v_sub_u32_e32 v11, v7, v9
	v_sub_u32_e32 v12, v19, v9
	v_max3_u32 v10, v12, v11, v10
	s_nop 1
	v_max_u32_dpp v10, v10, v10 quad_perm:[1,0,3,2] row_mask:0xf bank_mask:0xf bound_ctrl:1
	s_nop 1
	v_max_u32_dpp v10, v10, v10 quad_perm:[2,3,0,1] row_mask:0xf bank_mask:0xf bound_ctrl:1
	s_nop 1
	v_max_u32_dpp v10, v10, v10 row_half_mirror row_mask:0xf bank_mask:0xf bound_ctrl:1
	v_add_u32_e32 v11, v10, v9
	v_mov_b32_e32 v10, 0
	v_mov_b32_e32 v9, 0
	s_and_saveexec_b64 s[34:35], s[46:47]
	v_and_b32_e32 v9, 0x7fffffc0, v11
	v_bitop3_b32 v10, v11, 63, v11 bitop3:0xcf
	v_cmp_gt_i32_e64 s[46:47], 0, v11
	s_nop 1
	v_cndmask_b32_e64 v10, v10, v9, s[46:47]
	v_bitop3_b32 v9, v11, 63, v11 bitop3:0xc
	s_or_b64 exec, exec, s[34:35]
	v_sub_u32_e32 v12, v2, v11
	v_sub_u32_e32 v13, v4, v11
	v_sub_u32_e32 v20, v3, v11
	v_max3_u32 v12, v20, v13, v12
	v_sub_u32_e32 v13, v5, v11
	v_sub_u32_e32 v20, v6, v11
	v_max3_u32 v12, v20, v13, v12
	v_sub_u32_e32 v13, v7, v11
	v_sub_u32_e32 v20, v19, v11
	v_max3_u32 v12, v20, v13, v12
	s_nop 1
	v_max_u32_dpp v12, v12, v12 quad_perm:[1,0,3,2] row_mask:0xf bank_mask:0xf bound_ctrl:1
	s_nop 1
	v_max_u32_dpp v12, v12, v12 quad_perm:[2,3,0,1] row_mask:0xf bank_mask:0xf bound_ctrl:1
	s_nop 1
	v_max_u32_dpp v12, v12, v12 row_half_mirror row_mask:0xf bank_mask:0xf bound_ctrl:1
	v_add_u32_e32 v11, v12, v11
	s_and_saveexec_b64 s[34:35], vcc
	v_and_b32_e32 v9, 0x7fffffc0, v11
	v_bitop3_b32 v10, v11, 63, v11 bitop3:0xcf
	v_cmp_gt_i32_e32 vcc, 0, v11
	s_nop 1
	v_cndmask_b32_e32 v10, v10, v9, vcc
	v_bitop3_b32 v9, v11, 63, v11 bitop3:0xc
	s_or_b64 exec, exec, s[34:35]
	v_sub_u32_e32 v12, v2, v11
	v_sub_u32_e32 v13, v4, v11
	v_sub_u32_e32 v20, v3, v11
	v_max3_u32 v12, v20, v13, v12
	v_sub_u32_e32 v13, v5, v11
	v_sub_u32_e32 v20, v6, v11
	v_max3_u32 v12, v20, v13, v12
	v_sub_u32_e32 v13, v7, v11
	v_sub_u32_e32 v20, v19, v11
	v_max3_u32 v12, v20, v13, v12
	s_nop 1
	v_max_u32_dpp v12, v12, v12 quad_perm:[1,0,3,2] row_mask:0xf bank_mask:0xf bound_ctrl:1
	s_nop 1
	v_max_u32_dpp v12, v12, v12 quad_perm:[2,3,0,1] row_mask:0xf bank_mask:0xf bound_ctrl:1
	s_nop 1
	v_max_u32_dpp v12, v12, v12 row_half_mirror row_mask:0xf bank_mask:0xf bound_ctrl:1
	v_add_u32_e32 v11, v12, v11
	s_and_saveexec_b64 s[34:35], s[0:1]
	v_and_b32_e32 v9, 0x7fffffc0, v11
	v_bitop3_b32 v10, v11, 63, v11 bitop3:0xcf
	v_cmp_gt_i32_e32 vcc, 0, v11
	s_nop 1
	v_cndmask_b32_e32 v10, v10, v9, vcc
	v_bitop3_b32 v9, v11, 63, v11 bitop3:0xc
	s_or_b64 exec, exec, s[34:35]
	v_sub_u32_e32 v12, v2, v11
	v_sub_u32_e32 v13, v4, v11
	v_sub_u32_e32 v20, v3, v11
	v_max3_u32 v12, v20, v13, v12
	v_sub_u32_e32 v13, v5, v11
	v_sub_u32_e32 v20, v6, v11
	v_max3_u32 v12, v20, v13, v12
	v_sub_u32_e32 v13, v7, v11
	v_sub_u32_e32 v20, v19, v11
	v_max3_u32 v12, v20, v13, v12
	s_nop 1
	v_max_u32_dpp v12, v12, v12 quad_perm:[1,0,3,2] row_mask:0xf bank_mask:0xf bound_ctrl:1
	s_nop 1
	v_max_u32_dpp v12, v12, v12 quad_perm:[2,3,0,1] row_mask:0xf bank_mask:0xf bound_ctrl:1
	s_nop 1
	v_max_u32_dpp v12, v12, v12 row_half_mirror row_mask:0xf bank_mask:0xf bound_ctrl:1
	v_add_u32_e32 v11, v12, v11
	s_and_saveexec_b64 s[0:1], s[36:37]
	v_and_b32_e32 v9, 0x7fffffc0, v11
	v_bitop3_b32 v10, v11, 63, v11 bitop3:0xcf
	v_cmp_gt_i32_e32 vcc, 0, v11
	s_nop 1
	v_cndmask_b32_e32 v10, v10, v9, vcc
	v_bitop3_b32 v9, v11, 63, v11 bitop3:0xc
	s_or_b64 exec, exec, s[0:1]
	v_sub_u32_e32 v12, v2, v11
	v_sub_u32_e32 v13, v4, v11
	v_sub_u32_e32 v20, v3, v11
	v_max3_u32 v12, v20, v13, v12
	v_sub_u32_e32 v13, v5, v11
	v_sub_u32_e32 v20, v6, v11
	v_max3_u32 v12, v20, v13, v12
	v_sub_u32_e32 v13, v7, v11
	v_sub_u32_e32 v20, v19, v11
	v_max3_u32 v12, v20, v13, v12
	s_nop 1
	v_max_u32_dpp v12, v12, v12 quad_perm:[1,0,3,2] row_mask:0xf bank_mask:0xf bound_ctrl:1
	s_nop 1
	v_max_u32_dpp v12, v12, v12 quad_perm:[2,3,0,1] row_mask:0xf bank_mask:0xf bound_ctrl:1
	s_nop 1
; template <int CTRL> DI int dpp_i(int v) { return __builtin_amdgcn_mov_dpp(v, CTRL, 0xF, 0xF, true); }
; template <int CTRL> DI float dpp_f(float v) { return __builtin_bit_cast(float, __builtin_amdgcn_mov_dpp(__builtin_bit_cast(int, v), CTRL, 0xF, 0xF, true)); }
; DI void phase_peer(const Params& p, int l, int bid, int nblk) {
;     ...
; #pragma unroll
;     for (int r = 0; r < 16; ++r) {
;       u32 m = 0u;
; #pragma unroll
;       for (int s = 0; s < 7; ++s) { const u32 d = ck[s] - prevk; m = d > m ? d : m; }
;       { const u32 ov = (u32)dpp_i<DPP_XOR1>((int)m); m = ov > m ? ov : m; }
;       { const u32 ov = (u32)dpp_i<DPP_XOR2>((int)m); m = ov > m ? ov : m; }
;       { const u32 ov = (u32)dpp_i<DPP_MIRROR8>((int)m); m = ov > m ? ov : m; }
;       const u32 best = prevk + m;
;       prevk = best;
;       const u32 ordv = best & ~63u;
;       const float bv = __uint_as_float((ordv & 0x80000000u) ? (ordv & 0x7FFFFFFFu) : ~ordv);
;       const int bc = 63 - (int)(best & 63u);
;       if (r == 0) mx = bv;
;       if (sub == (r & 7)) {
;         if (r < 8) { w0v = bv; w0c = bc; } else { w1v = bv; w1c = bc; }
;       }
;     }
;     const float e0 = expf(w0v - mx), e1 = expf(w1v - mx);
;     float es = e0 + e1;
;     es += dpp_f<DPP_XOR1>(es);
;     es += dpp_f<DPP_XOR2>(es);
;     es += dpp_f<DPP_MIRROR8>(es);
;     const float g0 = e0 / es, g1 = e1 / es;
;     int idx0, idx1;
;     {
;       const int gb = lane & ~7;
;       const int a0 = cand_a(w0c), c0 = cand_b(w0c), a1 = cand_a(w1c), c1 = cand_b(w1c);
;       const int p0l = __shfl(t1lo, gb + (a0 & 7)), p0h = __shfl(t1hi, gb + (a0 & 7));
;       const int q0l = __shfl(t2lo, gb + (c0 & 7)), q0h = __shfl(t2hi, gb + (c0 & 7));
;       const int p1l = __shfl(t1lo, gb + (a1 & 7)), p1h = __shfl(t1hi, gb + (a1 & 7));
;       const int q1l = __shfl(t2lo, gb + (c1 & 7)), q1h = __shfl(t2hi, gb + (c1 & 7));
;       idx0 = ((a0 & 8) ? p0h : p0l) * 128 + ((c0 & 8) ? q0h : q0l);
;       idx1 = ((a1 & 8) ? p1h : p1l) * 128 + ((c1 & 8) ? q1h : q1l);
	v_max_u32_dpp v12, v12, v12 row_half_mirror row_mask:0xf bank_mask:0xf bound_ctrl:1
	v_add_u32_e32 v11, v12, v11
	s_and_saveexec_b64 s[0:1], s[38:39]
	v_and_b32_e32 v9, 0x7fffffc0, v11
	v_bitop3_b32 v10, v11, 63, v11 bitop3:0xcf
	v_cmp_gt_i32_e32 vcc, 0, v11
	s_nop 1
	v_cndmask_b32_e32 v10, v10, v9, vcc
	v_bitop3_b32 v9, v11, 63, v11 bitop3:0xc
	s_or_b64 exec, exec, s[0:1]
	v_sub_u32_e32 v12, v2, v11
	v_sub_u32_e32 v13, v4, v11
	v_sub_u32_e32 v20, v3, v11
	v_max3_u32 v12, v20, v13, v12
	v_sub_u32_e32 v13, v5, v11
	v_sub_u32_e32 v20, v6, v11
	v_max3_u32 v12, v20, v13, v12
	v_sub_u32_e32 v13, v7, v11
	v_sub_u32_e32 v20, v19, v11
	v_max3_u32 v12, v20, v13, v12
	s_nop 1
	v_max_u32_dpp v12, v12, v12 quad_perm:[1,0,3,2] row_mask:0xf bank_mask:0xf bound_ctrl:1
	s_nop 1
	v_max_u32_dpp v12, v12, v12 quad_perm:[2,3,0,1] row_mask:0xf bank_mask:0xf bound_ctrl:1
	s_nop 1
	v_max_u32_dpp v12, v12, v12 row_half_mirror row_mask:0xf bank_mask:0xf bound_ctrl:1
	v_add_u32_e32 v11, v12, v11
	s_and_saveexec_b64 s[0:1], s[40:41]
	v_and_b32_e32 v9, 0x7fffffc0, v11
	v_bitop3_b32 v10, v11, 63, v11 bitop3:0xcf
	v_cmp_gt_i32_e32 vcc, 0, v11
	s_nop 1
	v_cndmask_b32_e32 v10, v10, v9, vcc
	v_bitop3_b32 v9, v11, 63, v11 bitop3:0xc
	s_or_b64 exec, exec, s[0:1]
	v_sub_u32_e32 v12, v2, v11
	v_sub_u32_e32 v13, v4, v11
	v_sub_u32_e32 v20, v3, v11
	v_max3_u32 v12, v20, v13, v12
	v_sub_u32_e32 v13, v5, v11
	v_sub_u32_e32 v20, v6, v11
	v_max3_u32 v12, v20, v13, v12
	v_sub_u32_e32 v13, v7, v11
	v_sub_u32_e32 v20, v19, v11
	v_max3_u32 v12, v20, v13, v12
	s_nop 1
	v_max_u32_dpp v12, v12, v12 quad_perm:[1,0,3,2] row_mask:0xf bank_mask:0xf bound_ctrl:1
	s_nop 1
	v_max_u32_dpp v12, v12, v12 quad_perm:[2,3,0,1] row_mask:0xf bank_mask:0xf bound_ctrl:1
	s_nop 1
	v_max_u32_dpp v12, v12, v12 row_half_mirror row_mask:0xf bank_mask:0xf bound_ctrl:1
	v_add_u32_e32 v11, v12, v11
	s_and_saveexec_b64 s[0:1], s[42:43]
	v_and_b32_e32 v9, 0x7fffffc0, v11
	v_bitop3_b32 v10, v11, 63, v11 bitop3:0xcf
	v_cmp_gt_i32_e32 vcc, 0, v11
	s_nop 1
	v_cndmask_b32_e32 v10, v10, v9, vcc
	v_bitop3_b32 v9, v11, 63, v11 bitop3:0xc
	s_or_b64 exec, exec, s[0:1]
	v_sub_u32_e32 v2, v2, v11
	v_sub_u32_e32 v4, v4, v11
	v_sub_u32_e32 v3, v3, v11
	v_max3_u32 v2, v3, v4, v2
	v_sub_u32_e32 v3, v5, v11
	v_sub_u32_e32 v4, v6, v11
	v_max3_u32 v2, v4, v3, v2
	v_sub_u32_e32 v3, v7, v11
	v_sub_u32_e32 v4, v19, v11
	v_max3_u32 v2, v4, v3, v2
	s_nop 1
	v_max_u32_dpp v2, v2, v2 quad_perm:[1,0,3,2] row_mask:0xf bank_mask:0xf bound_ctrl:1
	s_nop 1
	v_max_u32_dpp v2, v2, v2 quad_perm:[2,3,0,1] row_mask:0xf bank_mask:0xf bound_ctrl:1
	s_nop 1
	v_mov_b32_dpp v3, v2 row_half_mirror row_mask:0xf bank_mask:0xf bound_ctrl:1
	s_and_saveexec_b64 s[0:1], s[44:45]
	v_max_u32_e32 v2, v3, v2
	v_add_u32_e32 v2, v2, v11
	v_and_b32_e32 v3, 0x7fffffc0, v2
	v_bitop3_b32 v4, v2, 63, v2 bitop3:0xcf
	v_cmp_gt_i32_e32 vcc, 0, v2
	v_bitop3_b32 v9, v2, 63, v2 bitop3:0xc
	s_nop 0
	v_cndmask_b32_e32 v10, v4, v3, vcc
	s_or_b64 exec, exec, s[0:1]
	v_sub_f32_e32 v3, v8, v1
	v_mul_f32_e32 v4, 0x3fb8aa3b, v3
	v_fma_f32 v5, v3, s2, -v4
	v_rndne_f32_e32 v6, v4
	v_fmac_f32_e32 v5, 0x32a5705f, v3
	v_sub_f32_e32 v4, v4, v6
	v_add_f32_e32 v4, v4, v5
	v_exp_f32_e32 v4, v4
	v_cvt_i32_f32_e32 v5, v6
	v_cmp_ngt_f32_e32 vcc, s3, v3
	v_sub_f32_e32 v1, v10, v1
	v_mov_b32_e32 v8, 0x11111111
	v_ldexp_f32 v4, v4, v5
	v_cndmask_b32_e32 v4, 0, v4, vcc
	v_cmp_nlt_f32_e32 vcc, s58, v3
	v_mul_f32_e32 v3, 0x3fb8aa3b, v1
	v_rndne_f32_e32 v5, v3
	v_cndmask_b32_e32 v85, v217, v4, vcc
	v_fma_f32 v4, v1, s2, -v3
	v_fmac_f32_e32 v4, 0x32a5705f, v1
	v_sub_f32_e32 v3, v3, v5
	v_add_f32_e32 v3, v3, v4
	v_exp_f32_e32 v3, v3
	v_cvt_i32_f32_e32 v4, v5
	v_cmp_ngt_f32_e32 vcc, s3, v1
	v_mov_b32_e32 v19, 0x76543210
	v_mov_b32_e32 v20, 0xfedcba98
	v_ldexp_f32 v3, v3, v4
	v_cndmask_b32_e32 v3, 0, v3, vcc
	v_cmp_nlt_f32_e32 vcc, s58, v1
	v_mov_b32_e32 v10, 0x33322222
	v_mov_b32_e32 v21, 0x21043210
	v_cndmask_b32_e32 v86, v217, v3, vcc
	v_lshrrev_b32_e32 v3, 3, v0
	v_cmp_eq_u32_e32 vcc, 2, v3
	v_cmp_eq_u32_e64 s[40:41], 1, v3
	v_cmp_eq_u32_e64 s[0:1], 4, v3
	v_cndmask_b32_e32 v4, 0, v8, vcc
	v_cmp_eq_u32_e32 vcc, 3, v3
	v_cmp_eq_u32_e64 s[36:37], 5, v3
	v_cmp_eq_u32_e64 s[38:39], 6, v3
	v_cndmask_b32_e64 v3, v19, v20, s[40:41]
	v_cndmask_b32_e32 v4, v4, v10, vcc
	v_mov_b32_e32 v11, 0x66554443
	v_cndmask_b32_e32 v3, v3, v21, vcc
	v_mov_b32_e32 v22, 0x10102103
	v_lshrrev_b32_e32 v7, 3, v9
	v_cndmask_b32_e64 v4, v4, v11, s[0:1]
	v_mov_b32_e32 v12, 0xdcba9877
	v_cndmask_b32_e64 v3, v3, v22, s[0:1]
	v_cmp_eq_u32_e32 vcc, 2, v7
	v_cndmask_b32_e64 v4, v4, v12, s[36:37]
	v_mov_b32_e32 v13, 0xfe
	v_cndmask_b32_e64 v3, v3, 16, s[36:37]
	v_cndmask_b32_e32 v8, 0, v8, vcc
	v_cmp_eq_u32_e32 vcc, 3, v7
	v_cmp_eq_u32_e64 s[40:41], 1, v7
	v_add_f32_e32 v1, v85, v86
	v_cndmask_b32_e64 v4, v4, v13, s[38:39]
	v_lshlrev_b32_e32 v0, 2, v0
	v_cndmask_b32_e64 v3, v3, 0, s[38:39]
	v_cndmask_b32_e32 v8, v8, v10, vcc
	v_cmp_eq_u32_e64 s[0:1], 4, v7
	v_cmp_eq_u32_e64 s[36:37], 5, v7
	v_cmp_eq_u32_e64 s[38:39], 6, v7
	v_cndmask_b32_e64 v7, v19, v20, s[40:41]
	v_add_f32_dpp v1, v1, v1 quad_perm:[1,0,3,2] row_mask:0xf bank_mask:0xf bound_ctrl:1
	v_and_b32_e32 v5, 28, v0
	v_cndmask_b32_e64 v8, v8, v11, s[0:1]
	v_cndmask_b32_e32 v7, v7, v21, vcc
	v_add_f32_dpp v87, v1, v1 quad_perm:[2,3,0,1] row_mask:0xf bank_mask:0xf bound_ctrl:1
	v_and_b32_e32 v1, 56, v14
	v_lshrrev_b32_e32 v6, v0, v4
	v_cndmask_b32_e64 v8, v8, v12, s[36:37]
	v_lshlrev_b32_e32 v9, 2, v9
	v_cndmask_b32_e64 v7, v7, v22, s[0:1]
	v_bfe_u32 v4, v4, v5, 3
	v_lshrrev_b32_e32 v0, v0, v3
	v_cndmask_b32_e64 v8, v8, v13, s[38:39]
	v_and_b32_e32 v10, 28, v9
	v_cndmask_b32_e64 v7, v7, 16, s[36:37]
	v_or3_b32 v4, v1, v4, v216
	v_bfe_u32 v3, v3, v5, 3
	v_lshrrev_b32_e32 v11, v9, v8
	v_cndmask_b32_e64 v7, v7, 0, s[38:39]
	v_lshlrev_b32_e32 v4, 2, v4
	v_or3_b32 v3, v1, v3, v216
	v_bfe_u32 v8, v8, v10, 3
	v_lshrrev_b32_e32 v9, v9, v7
	ds_bpermute_b32 v12, v4, v17
	ds_bpermute_b32 v4, v4, v18
	v_lshlrev_b32_e32 v3, 2, v3
	v_or3_b32 v8, v1, v8, v216
	v_bfe_u32 v7, v7, v10, 3
	ds_bpermute_b32 v5, v3, v15
	ds_bpermute_b32 v3, v3, v16
	v_lshlrev_b32_e32 v8, 2, v8
	v_or3_b32 v1, v1, v7, v216
	ds_bpermute_b32 v13, v8, v17
	ds_bpermute_b32 v8, v8, v18
	v_lshlrev_b32_e32 v1, 2, v1
	v_and_b32_e32 v6, 8, v6
	ds_bpermute_b32 v7, v1, v15
	ds_bpermute_b32 v1, v1, v16
	v_and_b32_e32 v0, 8, v0
	v_cmp_eq_u32_e32 vcc, 0, v6
	v_and_b32_e32 v11, 8, v11
	v_and_b32_e32 v9, 8, v9
	s_waitcnt lgkmcnt(6)
; DI void phase_peer(const Params& p, int l, int bid, int nblk) {
;     ...
;     const float g0 = e0 / es, g1 = e1 / es;
;     int idx0, idx1;
;     {
;       const int gb = lane & ~7;
;       const int a0 = cand_a(w0c), c0 = cand_b(w0c), a1 = cand_a(w1c), c1 = cand_b(w1c);
;       const int p0l = __shfl(t1lo, gb + (a0 & 7)), p0h = __shfl(t1hi, gb + (a0 & 7));
;       const int q0l = __shfl(t2lo, gb + (c0 & 7)), q0h = __shfl(t2hi, gb + (c0 & 7));
;       const int p1l = __shfl(t1lo, gb + (a1 & 7)), p1h = __shfl(t1hi, gb + (a1 & 7));
;       const int q1l = __shfl(t2lo, gb + (c1 & 7)), q1h = __shfl(t2hi, gb + (c1 & 7));
;       idx0 = ((a0 & 8) ? p0h : p0l) * 128 + ((c0 & 8) ? q0h : q0l);
;       idx1 = ((a1 & 8) ? p1h : p1l) * 128 + ((c1 & 8) ? q1h : q1l);
;     }
	v_cndmask_b32_e32 v10, v4, v12, vcc
	v_cmp_eq_u32_e32 vcc, 0, v0
	v_and_b32_e32 v2, 63, v14
	v_lshlrev_b32_e32 v172, 4, v2
	s_waitcnt lgkmcnt(4)
	v_cndmask_b32_e32 v12, v3, v5, vcc
	v_cmp_eq_u32_e32 vcc, 0, v11
	v_lshlrev_b32_e32 v2, 5, v2
	v_mov_b32_e32 v3, v173
	s_waitcnt lgkmcnt(2)
	v_cndmask_b32_e32 v8, v8, v13, vcc
	v_cmp_eq_u32_e32 vcc, 0, v9
	v_lshl_add_u32 v150, v10, 7, v12
	v_readlane_b32 s0, v255, 40
	s_waitcnt lgkmcnt(0)
	v_cndmask_b32_e32 v9, v1, v7, vcc
	v_lshl_add_u32 v151, v8, 7, v9
	v_mov_b32_dpp v88, v87 row_half_mirror row_mask:0xf bank_mask:0xf bound_ctrl:1
	v_lshrrev_b32_e32 v6, 6, v218
	v_and_b32_e32 v7, 63, v218
	v_add_f32_e32 v0, v87, v88
	v_mul_u32_u24_e32 v6, 0x4800, v6
	v_rcp_f32_e32 v1, v0
	v_lshl_add_u32 v6, v7, 2, v6
	v_fma_f32 v2, -v0, v1, 2.0
	v_mul_f32_e32 v1, v1, v2
	v_mul_f32_e32 v1, 0x3e800000, v1
	v_add_u32_e32 v6, s66, v6
	v_mul_f32_e32 v2, v85, v1
	v_mul_f32_e32 v3, v86, v1
	v_lshlrev_b32_e32 v4, 7, v150
	v_lshlrev_b32_e32 v5, 7, v151
	v_lshlrev_b32_e32 v9, 9, v64
	ds_write_b32 v6, v4
	ds_write_b32 v6, v5 offset:256
	v_lshl_add_u32 v9, v7, 2, v9
	s_add_u32 s16, s96, 0x0
	s_addc_u32 s17, s97, 0
	s_mov_b32 s30, 1
	global_store_dword v9, v2, s[16:17]
	global_store_dword v9, v3, s[16:17] offset:256
	s_add_i32 s55, s55, 1
	s_addk_i32 s66, 0x200
	s_branch .LBB0_1508
